# c19: dense attention key loop role-split (matrix segment PV+QK / vector segment exp+cvt+staging), waves 4-7 one segment behind waves 0-3, static priority raise for waves 4-7
# baseline (speedup 1.0000x reference)
; #define ATA_LOAD(RK, RV, t) do { const size_t tb = (size_t)(t) * 64 * 128; RK[0] = *(const u32x4*)(Kb + tb + goff0); RV[0] = *(const u32x4*)(Vb + tb + goff0); } while (0)
; #define ATA_STORE(RK, RV, st) do { unsigned char* sb_ = smem + (st) * ATA_STAGE; *(u32x4*)(sb_ + ko0) = RK[0]; *(u32x4*)(sb_ + vo0) = RV[0]; } while (0)
; __device__ void attn_a_item(const Params& p, int item, int l, unsigned char* smem) {
;     int tid_ = threadIdx.x; asm volatile("" : "+v"(tid_));
;     const int tid = tid_, lane = tid & 63, w = __builtin_amdgcn_readfirstlane(tid >> 6), r32 = lane & 31, hi = lane >> 5;
;     const int b = item >> 8, r = item & 255, kvh = r >> 7, qblk = (r >> 2) & 31, hq = kvh * 4 + (r & 3);
;     float* lq = (float*)(smem + ATA_LQ) + w * 32;
;     bf16_t* QA = (bf16_t*)(p.ws + WS_QA);
;     const bf16_t* GA = (const bf16_t*)(p.ws + WS_GA);
;     const size_t tokq = (size_t)b * SEQ + qblk * 256 + w * 32;
;     bf16x8 qr[4];
; #pragma unroll
;     for (int ds = 0; ds < 4; ++ds) qr[ds] = *(const bf16x8*)(QA + (tokq + r32) * 512 + hq * 64 + ds * 16 + hi * 8);
;     const bf16_t* Kb = (const bf16_t*)(p.ws + WS_KA) + (size_t)b * SEQ * 128 + kvh * 64;
;     const bf16_t* Vb = (const bf16_t*)(p.ws + WS_VA) + (size_t)b * SEQ * 128 + kvh * 64;
;     const float nshift = -((const float*)(p.ws + WS_BND))[l];
;     f32x16 o0, o1;
; #pragma unroll
;     for (int i = 0; i < 16; ++i) { o0[i] = 0.f; o1[i] = 0.f; }
;     f32x4 la4 = (f32x4){0.f, 0.f, 0.f, 0.f};
;     constexpr int NT = SEQ / 64;
;     const int row0 = tid >> 3, ch0 = tid & 7;
;     const size_t goff0 = (size_t)row0 * 128 + ch0 * 8;
;     const int ko0 = row0 * 144 + ch0 * 16;
;     const int vo0 = 9216 + (ch0 >> 2) * 4096 + row0 * 64 + (ch0 & 3) * 16;
;     u32x4 rkA[1], rvA[1], rkB[1], rvB[1];
;     ...
;     __syncthreads();
;     ATA_LOAD(rkA, rvA, 0); ATA_LOAD(rkB, rvB, 1);
;     ATA_STORE(rkA, rvA, 0);
;     ATA_LOAD(rkA, rvA, 2);
;     __syncthreads();
;     for (int kt = 0; kt < NT; kt += 2) {
;         ATA_COMPUTE(0);
.LBB0_845:
	v_mov_b32_e32 v11, v210
	s_ashr_i32 s20, s49, 8
	v_readfirstlane_b32 s9, v11
	s_ashr_i32 s17, s9, 1
	s_ashr_i32 s21, s20, 31
	s_lshl_b32 s22, s49, 6
	s_bfe_u32 s12, s49, 0x10007
	s_andn2_b32 s17, s17, 31
	s_lshl_b64 s[18:19], s[20:21], 13
	s_and_b32 s9, s22, 0x1f00
	s_lshl_b32 s24, s12, 7
	s_ashr_i32 s16, s17, 31
	s_or_b32 s9, s18, s9
	s_add_u32 s9, s9, s17
	v_and_b32_e32 v153, 31, v11
	s_addc_u32 s16, s19, s16
	v_or_b32_e32 v0, s9, v153
	v_mov_b32_e32 v1, s16
	s_lshl_b32 s12, s12, 8
	s_and_b32 s18, s22, 0xc0
	v_lshlrev_b64 v[0:1], 10, v[0:1]
	s_or_b32 s18, s12, s18
	v_lshl_add_u64 v[0:1], s[36:37], 0, v[0:1]
	s_lshl_b32 s12, s18, 1
	s_lshl_b64 s[44:45], s[20:21], 21
	v_lshl_add_u64 v[0:1], v[0:1], 0, s[12:13]
	s_add_u32 s12, s11, s44
	s_addc_u32 s19, s46, s45
	v_bfe_u32 v152, v11, 5, 1
	s_add_u32 s20, s47, s44
	v_ashrrev_i32_e32 v8, 3, v11
	v_lshlrev_b32_e32 v80, 4, v152
	s_addc_u32 s21, s48, s45
	v_ashrrev_i32_e32 v9, 31, v8
	v_lshlrev_b32_e32 v23, 4, v11
	v_lshl_add_u64 v[0:1], v[0:1], 0, v[80:81]
	s_add_u32 s20, s20, s24
	v_and_b32_e32 v10, 0x70, v23
	v_lshlrev_b64 v[12:13], 8, v[8:9]
	global_load_dwordx4 v[82:85], v[0:1], off
	global_load_dwordx4 v[86:89], v[0:1], off offset:32
	global_load_dwordx4 v[90:93], v[0:1], off offset:64
	global_load_dwordx4 v[94:97], v[0:1], off offset:96
	s_addc_u32 s21, s21, 0
	v_or_b32_e32 v0, v12, v10
	v_mov_b32_e32 v1, v13
	v_lshl_add_u64 v[14:15], s[20:21], 0, v[0:1]
	s_add_u32 s22, s12, s24
	v_add_co_u32_e32 v18, vcc, s34, v14
	s_addc_u32 s23, s19, 0
	s_nop 0
	v_addc_co_u32_e32 v19, vcc, 0, v15, vcc
	s_mov_b32 s19, 0x8000
	global_load_dword v22, v81, s[38:39]
	s_barrier
	v_lshl_add_u64 v[16:17], s[22:23], 0, v[0:1]
	global_load_dwordx4 v[0:3], v[14:15], off
	global_load_dwordx4 v[4:7], v[16:17], off
	v_add_co_u32_e32 v14, vcc, s19, v14
	v_lshlrev_b32_e32 v9, 10, v11
	s_nop 0
	v_addc_co_u32_e32 v15, vcc, 0, v15, vcc
	v_add_co_u32_e32 v20, vcc, s34, v16
	v_and_b32_e32 v9, 0x1000, v9
	s_nop 0
	v_addc_co_u32_e32 v21, vcc, 0, v17, vcc
	v_add_co_u32_e32 v16, vcc, s19, v16
	v_lshlrev_b32_e32 v24, 1, v11
	s_nop 0
	v_addc_co_u32_e32 v17, vcc, 0, v17, vcc
	v_add_co_u32_e32 v26, vcc, s34, v14
	s_nop 1
	v_addc_co_u32_e32 v27, vcc, 0, v15, vcc
	v_add_co_u32_e32 v28, vcc, s34, v16
	s_nop 1
	v_addc_co_u32_e32 v29, vcc, 0, v17, vcc
	global_load_dwordx4 v[236:239], v[18:19], off
	global_load_dwordx4 v[240:243], v[20:21], off
	global_load_dwordx4 v[98:101], v[14:15], off
	global_load_dwordx4 v[106:109], v[16:17], off
	global_load_dwordx4 v[102:105], v[26:27], off
	global_load_dwordx4 v[110:113], v[28:29], off
	v_and_b32_e32 v16, 48, v23
	v_mad_u64_u32 v[14:15], s[20:21], v8, s3, v[10:11]
	v_lshl_or_b32 v8, v8, 6, v16
	v_lshlrev_b32_e32 v25, 3, v11
	v_add_u32_e32 v155, 0, v14
	v_add_u32_e32 v8, v8, v9
	v_and_b32_e32 v18, 32, v24
	v_add_u32_e32 v156, 0, v8
	v_mul_u32_u24_e32 v17, 0x48, v153
	v_lshlrev_b32_e32 v15, 1, v17
	v_mov_b32_e32 v116, 0
	s_mov_b32 s12, 0
	v_and_b32_e32 v154, 63, v11
	v_add3_u32 v80, 0, v15, v80
	v_mov_b32_e32 v117, v116
	v_mov_b32_e32 v118, v116
	v_mov_b32_e32 v119, v116
	v_mov_b32_e32 v8, v116
	v_mov_b32_e32 v9, v116
	v_mov_b32_e32 v14, v116
	v_mov_b32_e32 v15, v116
	v_mov_b32_e32 v16, v116
	v_mov_b32_e32 v17, v116
	s_waitcnt vmcnt(7)
	ds_write_b128 v155, v[0:3]
	s_waitcnt vmcnt(6)
	ds_write_b128 v156, v[4:7] offset:9216
	s_waitcnt vmcnt(5)
	ds_write_b128 v155, v[236:239] offset:17408
	s_waitcnt vmcnt(4)
	ds_write_b128 v156, v[240:243] offset:26624
	v_and_b32_e32 v0, 24, v25
	v_add3_u32 v2, 0, v18, v0
	v_lshrrev_b32_e32 v0, 3, v11
	v_bfe_u32 v1, v11, 2, 2
	v_and_or_b32 v0, v0, 4, v1
	v_lshlrev_b32_e32 v3, 6, v0
	v_lshl_add_u64 v[0:1], s[44:45], 0, v[12:13]
	v_xor_b32_e32 v32, 0x80000000, v22
	v_or3_b32 v0, v0, s24, v10
	v_mov_b32_e32 v33, v32
	v_mov_b32_e32 v34, v32
	v_mov_b32_e32 v35, v32
	v_mov_b32_e32 v36, v32
	v_mov_b32_e32 v37, v32
	v_mov_b32_e32 v38, v32
	v_mov_b32_e32 v39, v32
	v_mov_b32_e32 v40, v32
	v_mov_b32_e32 v41, v32
	v_mov_b32_e32 v42, v32
	v_mov_b32_e32 v43, v32
	v_mov_b32_e32 v44, v32
	v_mov_b32_e32 v45, v32
	v_mov_b32_e32 v46, v32
	v_mov_b32_e32 v47, v32
	v_lshl_add_u64 v[114:115], s[42:43], 0, v[0:1]
	v_add_u32_e32 v157, v2, v3
	v_add_u32_e32 v209, 0x8800, v157
	v_add_u32_e32 v208, 0x8800, v80
	s_mov_b64 s[98:99], 0x4000
	v_mov_b32_e32 v0, v116
	v_mov_b32_e32 v1, v116
	v_mov_b32_e32 v2, v116
	v_mov_b32_e32 v3, v116
	v_mov_b32_e32 v4, v116
	v_mov_b32_e32 v5, v116
	v_mov_b32_e32 v6, v116
	v_mov_b32_e32 v7, v116
	v_mov_b32_e32 v10, v116
	v_mov_b32_e32 v11, v116
	v_mov_b32_e32 v12, v116
	v_mov_b32_e32 v13, v116
	v_mov_b32_e32 v18, v116
	v_mov_b32_e32 v19, v116
	v_mov_b32_e32 v20, v116
	v_mov_b32_e32 v21, v116
	v_mov_b32_e32 v22, v116
	v_mov_b32_e32 v23, v116
	v_mov_b32_e32 v24, v116
	v_mov_b32_e32 v25, v116
	v_mov_b32_e32 v26, v116
	v_mov_b32_e32 v27, v116
	v_mov_b32_e32 v28, v116
	v_mov_b32_e32 v29, v116
	v_mov_b32_e32 v30, v116
	v_mov_b32_e32 v31, v116
	s_waitcnt lgkmcnt(0)
	s_barrier
	v_readfirstlane_b32 s100, v210
	s_cmpk_lt_u32 s100, 0x100
	s_cbranch_scc1 .Lst_lead
	s_barrier
.Lst_lead:
	s_cmpk_lt_u32 s100, 0x100
	s_cbranch_scc1 .Lst_np
	s_setprio 1
.Lst_np:
	ds_read_b128 v[120:123], v80
	ds_read_b128 v[124:127], v80 offset:32
	ds_read_b128 v[128:131], v80 offset:64
	ds_read_b128 v[132:135], v80 offset:96
	ds_read_b128 v[136:139], v80 offset:4608
	ds_read_b128 v[140:143], v80 offset:4640
	ds_read_b128 v[144:147], v80 offset:4672
	ds_read_b128 v[148:151], v80 offset:4704
	s_waitcnt lgkmcnt(0)
	v_mfma_f32_32x32x16_bf16 v[48:63], v[120:123], v[82:85], v[32:47]
	v_mfma_f32_32x32x16_bf16 v[64:79], v[136:139], v[82:85], v[32:47]
	v_mfma_f32_32x32x16_bf16 v[48:63], v[124:127], v[86:89], v[48:63]
	v_mfma_f32_32x32x16_bf16 v[64:79], v[140:143], v[86:89], v[64:79]
	v_mfma_f32_32x32x16_bf16 v[48:63], v[128:131], v[90:93], v[48:63]
	v_mfma_f32_32x32x16_bf16 v[64:79], v[144:147], v[90:93], v[64:79]
	v_mfma_f32_32x32x16_bf16 v[48:63], v[132:135], v[94:97], v[48:63]
	v_mfma_f32_32x32x16_bf16 v[64:79], v[148:151], v[94:97], v[64:79]
	s_barrier
; __device__ __forceinline__ unsigned pk2(float lo, float hi) { f32x2 v = {lo, hi}; bf16x2_t b = __builtin_convertvector(v, bf16x2_t); return __builtin_bit_cast(unsigned, b); }
; __device__ __forceinline__ void at_ldv(bf16x8 (&v0)[4], bf16x8 (&v1)[4], const unsigned char* Vs, int lane) {
;     const int hi = lane >> 5;
;     const unsigned char* vb = Vs + ((lane >> 4) & 1) * 32 + (lane & 3) * 8 + (4 * hi + ((lane & 15) >> 2)) * 64;
; #pragma unroll
;     for (int s = 0; s < 4; ++s) {
;         v0[s] = cat8(tr16(vb + s * 1024), tr16(vb + s * 1024 + 512));
;         v1[s] = cat8(tr16(vb + 4096 + s * 1024), tr16(vb + 4096 + s * 1024 + 512));
;     }
; }
; __device__ __forceinline__ void at_pv2(f32x16& o0, f32x16& o1, const f32x16& p0, const f32x16& p1, const bf16x8 (&v0)[4], const bf16x8 (&v1)[4]) {
;     bf16x8 pa[4];
; #pragma unroll
;     for (int s = 0; s < 4; ++s) {
;         u32x4 pw;
;         if (s < 2) { pw.x = pk2(p0[8 * s + 0], p0[8 * s + 1]); pw.y = pk2(p0[8 * s + 2], p0[8 * s + 3]); pw.z = pk2(p0[8 * s + 4], p0[8 * s + 5]); pw.w = pk2(p0[8 * s + 6], p0[8 * s + 7]); }
;         else { const int q = s - 2; pw.x = pk2(p1[8 * q + 0], p1[8 * q + 1]); pw.y = pk2(p1[8 * q + 2], p1[8 * q + 3]); pw.z = pk2(p1[8 * q + 4], p1[8 * q + 5]); pw.w = pk2(p1[8 * q + 6], p1[8 * q + 7]); }
;         pa[s] = __builtin_bit_cast(bf16x8, pw);
;     }
;     __builtin_amdgcn_sched_barrier(0);
;     __builtin_amdgcn_s_setprio(1);
; #pragma unroll
;     for (int s = 0; s < 4; ++s) {
;         o0 = __builtin_amdgcn_mfma_f32_32x32x16_bf16(pa[s], v0[s], o0, 0, 0, 0);
;         o1 = __builtin_amdgcn_mfma_f32_32x32x16_bf16(pa[s], v1[s], o1, 0, 0, 0);
;     }
;     __builtin_amdgcn_s_setprio(0);
;     __builtin_amdgcn_sched_barrier(0);
; }
; __device__ void attn_a_item(const Params& p, int item, int l, unsigned char* smem) {
;     ...
;     __syncthreads();
;     ATA_LOAD(rkA, rvA, 0); ATA_LOAD(rkB, rvB, 1);
;     ATA_STORE(rkA, rvA, 0);
;     ATA_LOAD(rkA, rvA, 2);
;     __syncthreads();
;     for (int kt = 0; kt < NT; kt += 2) {
;         ATA_COMPUTE(0);
;         ATA_STORE(rkB, rvB, 1);
;         if (kt + 3 < NT) ATA_LOAD(rkB, rvB, kt + 3);
;         __syncthreads();
;         ATA_COMPUTE(1);
;         if (kt + 2 < NT) { ATA_STORE(rkA, rvA, 0); if (kt + 4 < NT) ATA_LOAD(rkA, rvA, kt + 4); }
;         __syncthreads();
;     }
.Lst_loop:
	ds_read_b128 v[120:123], v80 offset:17408
	ds_read_b128 v[124:127], v80 offset:17440
	ds_read_b128 v[128:131], v80 offset:17472
	ds_read_b128 v[132:135], v80 offset:17504
	ds_read_b128 v[136:139], v80 offset:22016
	ds_read_b128 v[140:143], v80 offset:22048
	ds_read_b128 v[144:147], v80 offset:22080
	ds_read_b128 v[148:151], v80 offset:22112
	ds_read_b64_tr_b16 v[158:159], v157 offset:9216
	ds_read_b64_tr_b16 v[160:161], v157 offset:9728
	ds_read_b64_tr_b16 v[162:163], v157 offset:10240
	ds_read_b64_tr_b16 v[164:165], v157 offset:10752
	ds_read_b64_tr_b16 v[166:167], v157 offset:11264
	ds_read_b64_tr_b16 v[168:169], v157 offset:11776
	ds_read_b64_tr_b16 v[170:171], v157 offset:12288
	ds_read_b64_tr_b16 v[172:173], v157 offset:12800
	ds_read_b64_tr_b16 v[174:175], v157 offset:13312
	ds_read_b64_tr_b16 v[176:177], v157 offset:13824
	ds_read_b64_tr_b16 v[180:181], v157 offset:14336
	ds_read_b64_tr_b16 v[182:183], v157 offset:14848
	ds_read_b64_tr_b16 v[184:185], v157 offset:15360
	ds_read_b64_tr_b16 v[186:187], v157 offset:15872
	ds_read_b64_tr_b16 v[188:189], v157 offset:16384
	ds_read_b64_tr_b16 v[190:191], v157 offset:16896
	s_cmpk_lt_u32 s12, 126
	s_cbranch_scc0 .Lst_ns0
	s_cmpk_lt_u32 s12, 125
	s_cbranch_scc1 .Lst_w20
	s_waitcnt vmcnt(0)
	s_branch .Lst_wd0
.Lst_w20:
	s_waitcnt vmcnt(2)
.Lst_wd0:
	ds_write_b128 v155, v[98:101] offset:34816
	ds_write_b128 v156, v[106:109] offset:44032
	s_cmpk_lt_u32 s12, 124
	s_cbranch_scc0 .Lst_ns0
	v_add_co_u32_e32 v230, vcc, 0xffc00000, v114
	s_nop 1
	v_addc_co_u32_e32 v231, vcc, -1, v115, vcc
	global_load_dwordx4 v[98:101], v[230:231], off
	global_load_dwordx4 v[106:109], v[114:115], off
	v_lshl_add_u64 v[114:115], v[114:115], 0, s[98:99]
.Lst_ns0:
	v_exp_f32_e32 v48, v48
	v_exp_f32_e32 v49, v49
	v_exp_f32_e32 v50, v50
	v_exp_f32_e32 v51, v51
	v_exp_f32_e32 v52, v52
	v_exp_f32_e32 v53, v53
	v_exp_f32_e32 v54, v54
	v_exp_f32_e32 v55, v55
	v_exp_f32_e32 v56, v56
	v_exp_f32_e32 v57, v57
	v_exp_f32_e32 v58, v58
	v_exp_f32_e32 v59, v59
	v_exp_f32_e32 v60, v60
	v_exp_f32_e32 v61, v61
	v_exp_f32_e32 v62, v62
	v_exp_f32_e32 v63, v63
	v_exp_f32_e32 v64, v64
	v_exp_f32_e32 v65, v65
	v_exp_f32_e32 v66, v66
	v_exp_f32_e32 v67, v67
	v_exp_f32_e32 v68, v68
	v_exp_f32_e32 v69, v69
	v_exp_f32_e32 v70, v70
	v_exp_f32_e32 v71, v71
	v_exp_f32_e32 v72, v72
	v_exp_f32_e32 v73, v73
	v_exp_f32_e32 v74, v74
	v_exp_f32_e32 v75, v75
	v_exp_f32_e32 v76, v76
	v_exp_f32_e32 v77, v77
	v_exp_f32_e32 v78, v78
	v_exp_f32_e32 v79, v79
	v_cvt_pk_bf16_f32 v192, v48, v49
	v_cvt_pk_bf16_f32 v193, v50, v51
	v_cvt_pk_bf16_f32 v194, v52, v53
	v_cvt_pk_bf16_f32 v195, v54, v55
	v_cvt_pk_bf16_f32 v196, v56, v57
	v_cvt_pk_bf16_f32 v197, v58, v59
	v_cvt_pk_bf16_f32 v198, v60, v61
	v_cvt_pk_bf16_f32 v199, v62, v63
	v_cvt_pk_bf16_f32 v200, v64, v65
	v_cvt_pk_bf16_f32 v201, v66, v67
	v_cvt_pk_bf16_f32 v202, v68, v69
	v_cvt_pk_bf16_f32 v203, v70, v71
	v_cvt_pk_bf16_f32 v204, v72, v73
	v_cvt_pk_bf16_f32 v205, v74, v75
	v_cvt_pk_bf16_f32 v206, v76, v77
	v_cvt_pk_bf16_f32 v207, v78, v79
	v_pk_add_f32 v[116:117], v[116:117], v[48:49]
	v_pk_add_f32 v[116:117], v[116:117], v[64:65]
	v_pk_add_f32 v[118:119], v[118:119], v[50:51]
	v_pk_add_f32 v[118:119], v[118:119], v[66:67]
	v_pk_add_f32 v[116:117], v[116:117], v[52:53]
	v_pk_add_f32 v[116:117], v[116:117], v[68:69]
	v_pk_add_f32 v[118:119], v[118:119], v[54:55]
	v_pk_add_f32 v[118:119], v[118:119], v[70:71]
	v_pk_add_f32 v[116:117], v[116:117], v[56:57]
	v_pk_add_f32 v[116:117], v[116:117], v[72:73]
	v_pk_add_f32 v[118:119], v[118:119], v[58:59]
	v_pk_add_f32 v[118:119], v[118:119], v[74:75]
	v_pk_add_f32 v[116:117], v[116:117], v[60:61]
	v_pk_add_f32 v[116:117], v[116:117], v[76:77]
	v_pk_add_f32 v[118:119], v[118:119], v[62:63]
	v_pk_add_f32 v[118:119], v[118:119], v[78:79]
	s_waitcnt lgkmcnt(0)
	s_barrier
	v_mfma_f32_32x32x16_bf16 v[0:15], v[192:195], v[158:161], v[0:15]
	v_mfma_f32_32x32x16_bf16 v[16:31], v[192:195], v[174:177], v[16:31]
	v_mfma_f32_32x32x16_bf16 v[0:15], v[196:199], v[162:165], v[0:15]
	v_mfma_f32_32x32x16_bf16 v[16:31], v[196:199], v[180:183], v[16:31]
	v_mfma_f32_32x32x16_bf16 v[0:15], v[200:203], v[166:169], v[0:15]
	v_mfma_f32_32x32x16_bf16 v[16:31], v[200:203], v[184:187], v[16:31]
	v_mfma_f32_32x32x16_bf16 v[0:15], v[204:207], v[170:173], v[0:15]
	v_mfma_f32_32x32x16_bf16 v[16:31], v[204:207], v[188:191], v[16:31]
	v_mfma_f32_32x32x16_bf16 v[48:63], v[120:123], v[82:85], v[32:47]
	v_mfma_f32_32x32x16_bf16 v[64:79], v[136:139], v[82:85], v[32:47]
	v_mfma_f32_32x32x16_bf16 v[48:63], v[124:127], v[86:89], v[48:63]
	v_mfma_f32_32x32x16_bf16 v[64:79], v[140:143], v[86:89], v[64:79]
	v_mfma_f32_32x32x16_bf16 v[48:63], v[128:131], v[90:93], v[48:63]
	v_mfma_f32_32x32x16_bf16 v[64:79], v[144:147], v[90:93], v[64:79]
	v_mfma_f32_32x32x16_bf16 v[48:63], v[132:135], v[94:97], v[48:63]
	v_mfma_f32_32x32x16_bf16 v[64:79], v[148:151], v[94:97], v[64:79]
	s_barrier
	ds_read_b128 v[120:123], v208
	ds_read_b128 v[124:127], v208 offset:32
	ds_read_b128 v[128:131], v208 offset:64
	ds_read_b128 v[132:135], v208 offset:96
	ds_read_b128 v[136:139], v208 offset:4608
	ds_read_b128 v[140:143], v208 offset:4640
	ds_read_b128 v[144:147], v208 offset:4672
	ds_read_b128 v[148:151], v208 offset:4704
	ds_read_b64_tr_b16 v[158:159], v157 offset:26624
	ds_read_b64_tr_b16 v[160:161], v157 offset:27136
	ds_read_b64_tr_b16 v[162:163], v157 offset:27648
	ds_read_b64_tr_b16 v[164:165], v157 offset:28160
	ds_read_b64_tr_b16 v[166:167], v157 offset:28672
	ds_read_b64_tr_b16 v[168:169], v157 offset:29184
	ds_read_b64_tr_b16 v[170:171], v157 offset:29696
	ds_read_b64_tr_b16 v[172:173], v157 offset:30208
	ds_read_b64_tr_b16 v[174:175], v157 offset:30720
	ds_read_b64_tr_b16 v[176:177], v157 offset:31232
	ds_read_b64_tr_b16 v[180:181], v157 offset:31744
	ds_read_b64_tr_b16 v[182:183], v157 offset:32256
	ds_read_b64_tr_b16 v[184:185], v157 offset:32768
	ds_read_b64_tr_b16 v[186:187], v157 offset:33280
	ds_read_b64_tr_b16 v[188:189], v157 offset:33792
	ds_read_b64_tr_b16 v[190:191], v157 offset:34304
	s_cmpk_lt_u32 s12, 125
	s_cbranch_scc0 .Lst_ns1
	s_cmpk_lt_u32 s12, 124
	s_cbranch_scc1 .Lst_w21
	s_waitcnt vmcnt(0)
	s_branch .Lst_wd1

; __device__ __forceinline__ unsigned pk2(float lo, float hi) { f32x2 v = {lo, hi}; bf16x2_t b = __builtin_convertvector(v, bf16x2_t); return __builtin_bit_cast(unsigned, b); }
; __device__ __forceinline__ void at_ldv(bf16x8 (&v0)[4], bf16x8 (&v1)[4], const unsigned char* Vs, int lane) {
;     const int hi = lane >> 5;
;     const unsigned char* vb = Vs + ((lane >> 4) & 1) * 32 + (lane & 3) * 8 + (4 * hi + ((lane & 15) >> 2)) * 64;
; #pragma unroll
;     for (int s = 0; s < 4; ++s) {
;         v0[s] = cat8(tr16(vb + s * 1024), tr16(vb + s * 1024 + 512));
;         v1[s] = cat8(tr16(vb + 4096 + s * 1024), tr16(vb + 4096 + s * 1024 + 512));
;     }
; }
; __device__ __forceinline__ void at_pv2(f32x16& o0, f32x16& o1, const f32x16& p0, const f32x16& p1, const bf16x8 (&v0)[4], const bf16x8 (&v1)[4]) {
;     bf16x8 pa[4];
; #pragma unroll
;     for (int s = 0; s < 4; ++s) {
;         u32x4 pw;
;         if (s < 2) { pw.x = pk2(p0[8 * s + 0], p0[8 * s + 1]); pw.y = pk2(p0[8 * s + 2], p0[8 * s + 3]); pw.z = pk2(p0[8 * s + 4], p0[8 * s + 5]); pw.w = pk2(p0[8 * s + 6], p0[8 * s + 7]); }
;         else { const int q = s - 2; pw.x = pk2(p1[8 * q + 0], p1[8 * q + 1]); pw.y = pk2(p1[8 * q + 2], p1[8 * q + 3]); pw.z = pk2(p1[8 * q + 4], p1[8 * q + 5]); pw.w = pk2(p1[8 * q + 6], p1[8 * q + 7]); }
;         pa[s] = __builtin_bit_cast(bf16x8, pw);
;     }
;     __builtin_amdgcn_sched_barrier(0);
;     __builtin_amdgcn_s_setprio(1);
; #pragma unroll
;     for (int s = 0; s < 4; ++s) {
;         o0 = __builtin_amdgcn_mfma_f32_32x32x16_bf16(pa[s], v0[s], o0, 0, 0, 0);
;         o1 = __builtin_amdgcn_mfma_f32_32x32x16_bf16(pa[s], v1[s], o1, 0, 0, 0);
;     }
;     __builtin_amdgcn_s_setprio(0);
;     __builtin_amdgcn_sched_barrier(0);
; }
; __device__ void attn_a_item(const Params& p, int item, int l, unsigned char* smem) {
;     ...
;     __syncthreads();
;     ATA_LOAD(rkA, rvA, 0); ATA_LOAD(rkB, rvB, 1);
;     ATA_STORE(rkA, rvA, 0);
;     ATA_LOAD(rkA, rvA, 2);
;     __syncthreads();
;     for (int kt = 0; kt < NT; kt += 2) {
;         ATA_COMPUTE(0);
;         ATA_STORE(rkB, rvB, 1);
;         if (kt + 3 < NT) ATA_LOAD(rkB, rvB, kt + 3);
;         __syncthreads();
;         ATA_COMPUTE(1);
;         if (kt + 2 < NT) { ATA_STORE(rkA, rvA, 0); if (kt + 4 < NT) ATA_LOAD(rkA, rvA, kt + 4); }
;         __syncthreads();
;     }
.Lst_wd1:
	ds_write_b128 v155, v[102:105] offset:52224
	ds_write_b128 v156, v[110:113] offset:61440
	s_cmpk_lt_u32 s12, 123
	s_cbranch_scc0 .Lst_ns1
	v_add_co_u32_e32 v230, vcc, 0xffc00000, v114
	s_nop 1
	v_addc_co_u32_e32 v231, vcc, -1, v115, vcc
	global_load_dwordx4 v[102:105], v[230:231], off
	global_load_dwordx4 v[110:113], v[114:115], off
	v_lshl_add_u64 v[114:115], v[114:115], 0, s[98:99]
.Lst_ns1:
	v_exp_f32_e32 v48, v48
	v_exp_f32_e32 v49, v49
	v_exp_f32_e32 v50, v50
	v_exp_f32_e32 v51, v51
	v_exp_f32_e32 v52, v52
	v_exp_f32_e32 v53, v53
	v_exp_f32_e32 v54, v54
	v_exp_f32_e32 v55, v55
	v_exp_f32_e32 v56, v56
	v_exp_f32_e32 v57, v57
	v_exp_f32_e32 v58, v58
	v_exp_f32_e32 v59, v59
	v_exp_f32_e32 v60, v60
	v_exp_f32_e32 v61, v61
	v_exp_f32_e32 v62, v62
	v_exp_f32_e32 v63, v63
	v_exp_f32_e32 v64, v64
	v_exp_f32_e32 v65, v65
	v_exp_f32_e32 v66, v66
	v_exp_f32_e32 v67, v67
	v_exp_f32_e32 v68, v68
	v_exp_f32_e32 v69, v69
	v_exp_f32_e32 v70, v70
	v_exp_f32_e32 v71, v71
	v_exp_f32_e32 v72, v72
	v_exp_f32_e32 v73, v73
	v_exp_f32_e32 v74, v74
	v_exp_f32_e32 v75, v75
	v_exp_f32_e32 v76, v76
	v_exp_f32_e32 v77, v77
	v_exp_f32_e32 v78, v78
	v_exp_f32_e32 v79, v79
	v_cvt_pk_bf16_f32 v192, v48, v49
	v_cvt_pk_bf16_f32 v193, v50, v51
	v_cvt_pk_bf16_f32 v194, v52, v53
	v_cvt_pk_bf16_f32 v195, v54, v55
	v_cvt_pk_bf16_f32 v196, v56, v57
	v_cvt_pk_bf16_f32 v197, v58, v59
	v_cvt_pk_bf16_f32 v198, v60, v61
	v_cvt_pk_bf16_f32 v199, v62, v63
	v_cvt_pk_bf16_f32 v200, v64, v65
	v_cvt_pk_bf16_f32 v201, v66, v67
	v_cvt_pk_bf16_f32 v202, v68, v69
	v_cvt_pk_bf16_f32 v203, v70, v71
	v_cvt_pk_bf16_f32 v204, v72, v73
	v_cvt_pk_bf16_f32 v205, v74, v75
	v_cvt_pk_bf16_f32 v206, v76, v77
	v_cvt_pk_bf16_f32 v207, v78, v79
	v_pk_add_f32 v[116:117], v[116:117], v[48:49]
	v_pk_add_f32 v[116:117], v[116:117], v[64:65]
	v_pk_add_f32 v[118:119], v[118:119], v[50:51]
	v_pk_add_f32 v[118:119], v[118:119], v[66:67]
	v_pk_add_f32 v[116:117], v[116:117], v[52:53]
	v_pk_add_f32 v[116:117], v[116:117], v[68:69]
	v_pk_add_f32 v[118:119], v[118:119], v[54:55]
	v_pk_add_f32 v[118:119], v[118:119], v[70:71]
	v_pk_add_f32 v[116:117], v[116:117], v[56:57]
	v_pk_add_f32 v[116:117], v[116:117], v[72:73]
	v_pk_add_f32 v[118:119], v[118:119], v[58:59]
	v_pk_add_f32 v[118:119], v[118:119], v[74:75]
	v_pk_add_f32 v[116:117], v[116:117], v[60:61]
	v_pk_add_f32 v[116:117], v[116:117], v[76:77]
	v_pk_add_f32 v[118:119], v[118:119], v[62:63]
	v_pk_add_f32 v[118:119], v[118:119], v[78:79]
	s_waitcnt lgkmcnt(0)
	s_barrier
	v_mfma_f32_32x32x16_bf16 v[0:15], v[192:195], v[158:161], v[0:15]
	v_mfma_f32_32x32x16_bf16 v[16:31], v[192:195], v[174:177], v[16:31]
	v_mfma_f32_32x32x16_bf16 v[0:15], v[196:199], v[162:165], v[0:15]
	v_mfma_f32_32x32x16_bf16 v[16:31], v[196:199], v[180:183], v[16:31]
	v_mfma_f32_32x32x16_bf16 v[0:15], v[200:203], v[166:169], v[0:15]
	v_mfma_f32_32x32x16_bf16 v[16:31], v[200:203], v[184:187], v[16:31]
	v_mfma_f32_32x32x16_bf16 v[0:15], v[204:207], v[170:173], v[0:15]
	v_mfma_f32_32x32x16_bf16 v[16:31], v[204:207], v[188:191], v[16:31]
	v_mfma_f32_32x32x16_bf16 v[48:63], v[120:123], v[82:85], v[32:47]
	v_mfma_f32_32x32x16_bf16 v[64:79], v[136:139], v[82:85], v[32:47]
	v_mfma_f32_32x32x16_bf16 v[48:63], v[124:127], v[86:89], v[48:63]
	v_mfma_f32_32x32x16_bf16 v[64:79], v[140:143], v[86:89], v[64:79]
	v_mfma_f32_32x32x16_bf16 v[48:63], v[128:131], v[90:93], v[48:63]
	v_mfma_f32_32x32x16_bf16 v[64:79], v[144:147], v[90:93], v[64:79]
	v_mfma_f32_32x32x16_bf16 v[48:63], v[132:135], v[94:97], v[48:63]
	v_mfma_f32_32x32x16_bf16 v[64:79], v[148:151], v[94:97], v[64:79]
	s_barrier
	ds_read_b128 v[120:123], v208 offset:17408
	ds_read_b128 v[124:127], v208 offset:17440
	ds_read_b128 v[128:131], v208 offset:17472
	ds_read_b128 v[132:135], v208 offset:17504
	ds_read_b128 v[136:139], v208 offset:22016
	ds_read_b128 v[140:143], v208 offset:22048
	ds_read_b128 v[144:147], v208 offset:22080
	ds_read_b128 v[148:151], v208 offset:22112
	ds_read_b64_tr_b16 v[158:159], v209 offset:9216
	ds_read_b64_tr_b16 v[160:161], v209 offset:9728
	ds_read_b64_tr_b16 v[162:163], v209 offset:10240
	ds_read_b64_tr_b16 v[164:165], v209 offset:10752
	ds_read_b64_tr_b16 v[166:167], v209 offset:11264
	ds_read_b64_tr_b16 v[168:169], v209 offset:11776
	ds_read_b64_tr_b16 v[170:171], v209 offset:12288
	ds_read_b64_tr_b16 v[172:173], v209 offset:12800
	ds_read_b64_tr_b16 v[174:175], v209 offset:13312
	ds_read_b64_tr_b16 v[176:177], v209 offset:13824
	ds_read_b64_tr_b16 v[180:181], v209 offset:14336
	ds_read_b64_tr_b16 v[182:183], v209 offset:14848
	ds_read_b64_tr_b16 v[184:185], v209 offset:15360
	ds_read_b64_tr_b16 v[186:187], v209 offset:15872
	ds_read_b64_tr_b16 v[188:189], v209 offset:16384
	ds_read_b64_tr_b16 v[190:191], v209 offset:16896
	s_cmpk_lt_u32 s12, 124
	s_cbranch_scc0 .Lst_ns2
	s_cmpk_lt_u32 s12, 123
	s_cbranch_scc1 .Lst_w22
	s_waitcnt vmcnt(0)
	s_branch .Lst_wd2

; __device__ __forceinline__ unsigned pk2(float lo, float hi) { f32x2 v = {lo, hi}; bf16x2_t b = __builtin_convertvector(v, bf16x2_t); return __builtin_bit_cast(unsigned, b); }
; __device__ __forceinline__ void at_ldv(bf16x8 (&v0)[4], bf16x8 (&v1)[4], const unsigned char* Vs, int lane) {
;     const int hi = lane >> 5;
;     const unsigned char* vb = Vs + ((lane >> 4) & 1) * 32 + (lane & 3) * 8 + (4 * hi + ((lane & 15) >> 2)) * 64;
; #pragma unroll
;     for (int s = 0; s < 4; ++s) {
;         v0[s] = cat8(tr16(vb + s * 1024), tr16(vb + s * 1024 + 512));
;         v1[s] = cat8(tr16(vb + 4096 + s * 1024), tr16(vb + 4096 + s * 1024 + 512));
;     }
; }
; __device__ __forceinline__ void at_pv2(f32x16& o0, f32x16& o1, const f32x16& p0, const f32x16& p1, const bf16x8 (&v0)[4], const bf16x8 (&v1)[4]) {
;     bf16x8 pa[4];
; #pragma unroll
;     for (int s = 0; s < 4; ++s) {
;         u32x4 pw;
;         if (s < 2) { pw.x = pk2(p0[8 * s + 0], p0[8 * s + 1]); pw.y = pk2(p0[8 * s + 2], p0[8 * s + 3]); pw.z = pk2(p0[8 * s + 4], p0[8 * s + 5]); pw.w = pk2(p0[8 * s + 6], p0[8 * s + 7]); }
;         else { const int q = s - 2; pw.x = pk2(p1[8 * q + 0], p1[8 * q + 1]); pw.y = pk2(p1[8 * q + 2], p1[8 * q + 3]); pw.z = pk2(p1[8 * q + 4], p1[8 * q + 5]); pw.w = pk2(p1[8 * q + 6], p1[8 * q + 7]); }
;         pa[s] = __builtin_bit_cast(bf16x8, pw);
;     }
;     __builtin_amdgcn_sched_barrier(0);
;     __builtin_amdgcn_s_setprio(1);
; #pragma unroll
;     for (int s = 0; s < 4; ++s) {
;         o0 = __builtin_amdgcn_mfma_f32_32x32x16_bf16(pa[s], v0[s], o0, 0, 0, 0);
;         o1 = __builtin_amdgcn_mfma_f32_32x32x16_bf16(pa[s], v1[s], o1, 0, 0, 0);
;     }
;     __builtin_amdgcn_s_setprio(0);
;     __builtin_amdgcn_sched_barrier(0);
; }
; __device__ void attn_a_item(const Params& p, int item, int l, unsigned char* smem) {
;     ...
;     __syncthreads();
;     ATA_LOAD(rkA, rvA, 0); ATA_LOAD(rkB, rvB, 1);
;     ATA_STORE(rkA, rvA, 0);
;     ATA_LOAD(rkA, rvA, 2);
;     __syncthreads();
;     for (int kt = 0; kt < NT; kt += 2) {
;         ATA_COMPUTE(0);
;         ATA_STORE(rkB, rvB, 1);
;         if (kt + 3 < NT) ATA_LOAD(rkB, rvB, kt + 3);
;         __syncthreads();
;         ATA_COMPUTE(1);
;         if (kt + 2 < NT) { ATA_STORE(rkA, rvA, 0); if (kt + 4 < NT) ATA_LOAD(rkA, rvA, kt + 4); }
;         __syncthreads();
;     }
.Lst_wd2:
	ds_write_b128 v155, v[98:101]
	ds_write_b128 v156, v[106:109] offset:9216
	s_cmpk_lt_u32 s12, 122
	s_cbranch_scc0 .Lst_ns2
	v_add_co_u32_e32 v230, vcc, 0xffc00000, v114
	s_nop 1
	v_addc_co_u32_e32 v231, vcc, -1, v115, vcc
	global_load_dwordx4 v[98:101], v[230:231], off
	global_load_dwordx4 v[106:109], v[114:115], off
	v_lshl_add_u64 v[114:115], v[114:115], 0, s[98:99]
.Lst_ns2:
	v_exp_f32_e32 v48, v48
	v_exp_f32_e32 v49, v49
	v_exp_f32_e32 v50, v50
	v_exp_f32_e32 v51, v51
	v_exp_f32_e32 v52, v52
	v_exp_f32_e32 v53, v53
	v_exp_f32_e32 v54, v54
	v_exp_f32_e32 v55, v55
	v_exp_f32_e32 v56, v56
	v_exp_f32_e32 v57, v57
	v_exp_f32_e32 v58, v58
	v_exp_f32_e32 v59, v59
	v_exp_f32_e32 v60, v60
	v_exp_f32_e32 v61, v61
	v_exp_f32_e32 v62, v62
	v_exp_f32_e32 v63, v63
	v_exp_f32_e32 v64, v64
	v_exp_f32_e32 v65, v65
	v_exp_f32_e32 v66, v66
	v_exp_f32_e32 v67, v67
	v_exp_f32_e32 v68, v68
	v_exp_f32_e32 v69, v69
	v_exp_f32_e32 v70, v70
	v_exp_f32_e32 v71, v71
	v_exp_f32_e32 v72, v72
	v_exp_f32_e32 v73, v73
	v_exp_f32_e32 v74, v74
	v_exp_f32_e32 v75, v75
	v_exp_f32_e32 v76, v76
	v_exp_f32_e32 v77, v77
	v_exp_f32_e32 v78, v78
	v_exp_f32_e32 v79, v79
	v_cvt_pk_bf16_f32 v192, v48, v49
	v_cvt_pk_bf16_f32 v193, v50, v51
	v_cvt_pk_bf16_f32 v194, v52, v53
	v_cvt_pk_bf16_f32 v195, v54, v55
	v_cvt_pk_bf16_f32 v196, v56, v57
	v_cvt_pk_bf16_f32 v197, v58, v59
	v_cvt_pk_bf16_f32 v198, v60, v61
	v_cvt_pk_bf16_f32 v199, v62, v63
	v_cvt_pk_bf16_f32 v200, v64, v65
	v_cvt_pk_bf16_f32 v201, v66, v67
	v_cvt_pk_bf16_f32 v202, v68, v69
	v_cvt_pk_bf16_f32 v203, v70, v71
	v_cvt_pk_bf16_f32 v204, v72, v73
	v_cvt_pk_bf16_f32 v205, v74, v75
	v_cvt_pk_bf16_f32 v206, v76, v77
	v_cvt_pk_bf16_f32 v207, v78, v79
	v_pk_add_f32 v[116:117], v[116:117], v[48:49]
	v_pk_add_f32 v[116:117], v[116:117], v[64:65]
	v_pk_add_f32 v[118:119], v[118:119], v[50:51]
	v_pk_add_f32 v[118:119], v[118:119], v[66:67]
	v_pk_add_f32 v[116:117], v[116:117], v[52:53]
	v_pk_add_f32 v[116:117], v[116:117], v[68:69]
	v_pk_add_f32 v[118:119], v[118:119], v[54:55]
	v_pk_add_f32 v[118:119], v[118:119], v[70:71]
	v_pk_add_f32 v[116:117], v[116:117], v[56:57]
	v_pk_add_f32 v[116:117], v[116:117], v[72:73]
	v_pk_add_f32 v[118:119], v[118:119], v[58:59]
	v_pk_add_f32 v[118:119], v[118:119], v[74:75]
	v_pk_add_f32 v[116:117], v[116:117], v[60:61]
	v_pk_add_f32 v[116:117], v[116:117], v[76:77]
	v_pk_add_f32 v[118:119], v[118:119], v[62:63]
	v_pk_add_f32 v[118:119], v[118:119], v[78:79]
	s_waitcnt lgkmcnt(0)
	s_barrier
	v_mfma_f32_32x32x16_bf16 v[0:15], v[192:195], v[158:161], v[0:15]
	v_mfma_f32_32x32x16_bf16 v[16:31], v[192:195], v[174:177], v[16:31]
	v_mfma_f32_32x32x16_bf16 v[0:15], v[196:199], v[162:165], v[0:15]
	v_mfma_f32_32x32x16_bf16 v[16:31], v[196:199], v[180:183], v[16:31]
	v_mfma_f32_32x32x16_bf16 v[0:15], v[200:203], v[166:169], v[0:15]
	v_mfma_f32_32x32x16_bf16 v[16:31], v[200:203], v[184:187], v[16:31]
	v_mfma_f32_32x32x16_bf16 v[0:15], v[204:207], v[170:173], v[0:15]
	v_mfma_f32_32x32x16_bf16 v[16:31], v[204:207], v[188:191], v[16:31]
	v_mfma_f32_32x32x16_bf16 v[48:63], v[120:123], v[82:85], v[32:47]
	v_mfma_f32_32x32x16_bf16 v[64:79], v[136:139], v[82:85], v[32:47]
	v_mfma_f32_32x32x16_bf16 v[48:63], v[124:127], v[86:89], v[48:63]
	v_mfma_f32_32x32x16_bf16 v[64:79], v[140:143], v[86:89], v[64:79]
	v_mfma_f32_32x32x16_bf16 v[48:63], v[128:131], v[90:93], v[48:63]
	v_mfma_f32_32x32x16_bf16 v[64:79], v[144:147], v[90:93], v[64:79]
	v_mfma_f32_32x32x16_bf16 v[48:63], v[132:135], v[94:97], v[48:63]
	v_mfma_f32_32x32x16_bf16 v[64:79], v[148:151], v[94:97], v[64:79]
	s_barrier
	ds_read_b128 v[120:123], v80
	ds_read_b128 v[124:127], v80 offset:32
	ds_read_b128 v[128:131], v80 offset:64
	ds_read_b128 v[132:135], v80 offset:96
	ds_read_b128 v[136:139], v80 offset:4608
	ds_read_b128 v[140:143], v80 offset:4640
	ds_read_b128 v[144:147], v80 offset:4672
	ds_read_b128 v[148:151], v80 offset:4704
	ds_read_b64_tr_b16 v[158:159], v209 offset:26624
	ds_read_b64_tr_b16 v[160:161], v209 offset:27136
	ds_read_b64_tr_b16 v[162:163], v209 offset:27648
	ds_read_b64_tr_b16 v[164:165], v209 offset:28160
	ds_read_b64_tr_b16 v[166:167], v209 offset:28672
	ds_read_b64_tr_b16 v[168:169], v209 offset:29184
	ds_read_b64_tr_b16 v[170:171], v209 offset:29696
	ds_read_b64_tr_b16 v[172:173], v209 offset:30208
	ds_read_b64_tr_b16 v[174:175], v209 offset:30720
	ds_read_b64_tr_b16 v[176:177], v209 offset:31232
	ds_read_b64_tr_b16 v[180:181], v209 offset:31744
	ds_read_b64_tr_b16 v[182:183], v209 offset:32256
	ds_read_b64_tr_b16 v[184:185], v209 offset:32768
	ds_read_b64_tr_b16 v[186:187], v209 offset:33280
	ds_read_b64_tr_b16 v[188:189], v209 offset:33792
	ds_read_b64_tr_b16 v[190:191], v209 offset:34304
	s_cmpk_lt_u32 s12, 123
	s_cbranch_scc0 .Lst_ns3
	s_cmpk_lt_u32 s12, 122
	s_cbranch_scc1 .Lst_w23
	s_waitcnt vmcnt(0)
	s_branch .Lst_wd3

; #define ATA_LOAD(RK, RV, t) do { const size_t tb = (size_t)(t) * 64 * 128; RK[0] = *(const u32x4*)(Kb + tb + goff0); RV[0] = *(const u32x4*)(Vb + tb + goff0); } while (0)
; #define ATA_STORE(RK, RV, st) do { unsigned char* sb_ = smem + (st) * ATA_STAGE; *(u32x4*)(sb_ + ko0) = RK[0]; *(u32x4*)(sb_ + vo0) = RV[0]; } while (0)
; __device__ void attn_a_item(const Params& p, int item, int l, unsigned char* smem) {
;     ...
;     __syncthreads();
;     ATA_LOAD(rkA, rvA, 0); ATA_LOAD(rkB, rvB, 1);
;     ATA_STORE(rkA, rvA, 0);
;     ATA_LOAD(rkA, rvA, 2);
;     __syncthreads();
;     for (int kt = 0; kt < NT; kt += 2) {
;         ATA_COMPUTE(0);
;         ATA_STORE(rkB, rvB, 1);
;         if (kt + 3 < NT) ATA_LOAD(rkB, rvB, kt + 3);
;         __syncthreads();
;         ATA_COMPUTE(1);
;         if (kt + 2 < NT) { ATA_STORE(rkA, rvA, 0); if (kt + 4 < NT) ATA_LOAD(rkA, rvA, kt + 4); }
;         __syncthreads();
;     }
;     ...
;     float lacc = (la4.x + la4.y) + (la4.z + la4.w);
;     lacc += __shfl_xor(lacc, 32);
;     if (hi == 0) lq[r32] = lacc;
;     asm volatile("s_waitcnt lgkmcnt(0)" ::: "memory");
.Lst_wd3:
	ds_write_b128 v155, v[102:105] offset:17408
	ds_write_b128 v156, v[110:113] offset:26624
	s_cmpk_lt_u32 s12, 121
	s_cbranch_scc0 .Lst_ns3
	v_add_co_u32_e32 v230, vcc, 0xffc00000, v114
	s_nop 1
	v_addc_co_u32_e32 v231, vcc, -1, v115, vcc
	global_load_dwordx4 v[102:105], v[230:231], off
	global_load_dwordx4 v[110:113], v[114:115], off
	v_lshl_add_u64 v[114:115], v[114:115], 0, s[98:99]
.Lst_ns3:
	v_exp_f32_e32 v48, v48
	v_exp_f32_e32 v49, v49
	v_exp_f32_e32 v50, v50
	v_exp_f32_e32 v51, v51
	v_exp_f32_e32 v52, v52
	v_exp_f32_e32 v53, v53
	v_exp_f32_e32 v54, v54
	v_exp_f32_e32 v55, v55
	v_exp_f32_e32 v56, v56
	v_exp_f32_e32 v57, v57
	v_exp_f32_e32 v58, v58
	v_exp_f32_e32 v59, v59
	v_exp_f32_e32 v60, v60
	v_exp_f32_e32 v61, v61
	v_exp_f32_e32 v62, v62
	v_exp_f32_e32 v63, v63
	v_exp_f32_e32 v64, v64
	v_exp_f32_e32 v65, v65
	v_exp_f32_e32 v66, v66
	v_exp_f32_e32 v67, v67
	v_exp_f32_e32 v68, v68
	v_exp_f32_e32 v69, v69
	v_exp_f32_e32 v70, v70
	v_exp_f32_e32 v71, v71
	v_exp_f32_e32 v72, v72
	v_exp_f32_e32 v73, v73
	v_exp_f32_e32 v74, v74
	v_exp_f32_e32 v75, v75
	v_exp_f32_e32 v76, v76
	v_exp_f32_e32 v77, v77
	v_exp_f32_e32 v78, v78
	v_exp_f32_e32 v79, v79
	v_cvt_pk_bf16_f32 v192, v48, v49
	v_cvt_pk_bf16_f32 v193, v50, v51
	v_cvt_pk_bf16_f32 v194, v52, v53
	v_cvt_pk_bf16_f32 v195, v54, v55
	v_cvt_pk_bf16_f32 v196, v56, v57
	v_cvt_pk_bf16_f32 v197, v58, v59
	v_cvt_pk_bf16_f32 v198, v60, v61
	v_cvt_pk_bf16_f32 v199, v62, v63
	v_cvt_pk_bf16_f32 v200, v64, v65
	v_cvt_pk_bf16_f32 v201, v66, v67
	v_cvt_pk_bf16_f32 v202, v68, v69
	v_cvt_pk_bf16_f32 v203, v70, v71
	v_cvt_pk_bf16_f32 v204, v72, v73
	v_cvt_pk_bf16_f32 v205, v74, v75
	v_cvt_pk_bf16_f32 v206, v76, v77
	v_cvt_pk_bf16_f32 v207, v78, v79
	v_pk_add_f32 v[116:117], v[116:117], v[48:49]
	v_pk_add_f32 v[116:117], v[116:117], v[64:65]
	v_pk_add_f32 v[118:119], v[118:119], v[50:51]
	v_pk_add_f32 v[118:119], v[118:119], v[66:67]
	v_pk_add_f32 v[116:117], v[116:117], v[52:53]
	v_pk_add_f32 v[116:117], v[116:117], v[68:69]
	v_pk_add_f32 v[118:119], v[118:119], v[54:55]
	v_pk_add_f32 v[118:119], v[118:119], v[70:71]
	v_pk_add_f32 v[116:117], v[116:117], v[56:57]
	v_pk_add_f32 v[116:117], v[116:117], v[72:73]
	v_pk_add_f32 v[118:119], v[118:119], v[58:59]
	v_pk_add_f32 v[118:119], v[118:119], v[74:75]
	v_pk_add_f32 v[116:117], v[116:117], v[60:61]
	v_pk_add_f32 v[116:117], v[116:117], v[76:77]
	v_pk_add_f32 v[118:119], v[118:119], v[62:63]
	v_pk_add_f32 v[118:119], v[118:119], v[78:79]
	s_waitcnt lgkmcnt(0)
	s_barrier
	v_mfma_f32_32x32x16_bf16 v[0:15], v[192:195], v[158:161], v[0:15]
	v_mfma_f32_32x32x16_bf16 v[16:31], v[192:195], v[174:177], v[16:31]
	v_mfma_f32_32x32x16_bf16 v[0:15], v[196:199], v[162:165], v[0:15]
	v_mfma_f32_32x32x16_bf16 v[16:31], v[196:199], v[180:183], v[16:31]
	v_mfma_f32_32x32x16_bf16 v[0:15], v[200:203], v[166:169], v[0:15]
	v_mfma_f32_32x32x16_bf16 v[16:31], v[200:203], v[184:187], v[16:31]
	v_mfma_f32_32x32x16_bf16 v[0:15], v[204:207], v[170:173], v[0:15]
	v_mfma_f32_32x32x16_bf16 v[16:31], v[204:207], v[188:191], v[16:31]
	v_mfma_f32_32x32x16_bf16 v[48:63], v[120:123], v[82:85], v[32:47]
	v_mfma_f32_32x32x16_bf16 v[64:79], v[136:139], v[82:85], v[32:47]
	v_mfma_f32_32x32x16_bf16 v[48:63], v[124:127], v[86:89], v[48:63]
	v_mfma_f32_32x32x16_bf16 v[64:79], v[140:143], v[86:89], v[64:79]
	v_mfma_f32_32x32x16_bf16 v[48:63], v[128:131], v[90:93], v[48:63]
	v_mfma_f32_32x32x16_bf16 v[64:79], v[144:147], v[90:93], v[64:79]
	v_mfma_f32_32x32x16_bf16 v[48:63], v[132:135], v[94:97], v[48:63]
	v_mfma_f32_32x32x16_bf16 v[64:79], v[148:151], v[94:97], v[64:79]
	s_barrier
	s_add_i32 s12, s12, 4
	s_cmpk_lt_u32 s12, 0x80
	s_cbranch_scc1 .Lst_loop
	s_setprio 0
	s_cmpk_lt_u32 s100, 0x100
	s_cbranch_scc0 .Lst_end
	s_barrier
.Lst_end:
.LBB0_852:
	v_add_f32_e32 v32, v116, v117
	v_add_f32_e32 v33, v118, v119
	v_cmp_lt_i32_e32 vcc, v223, v217
	v_add_f32_e32 v32, v32, v33
	s_lshl_b32 s12, s17, 2
	v_cndmask_b32_e32 v33, v216, v223, vcc
	v_lshlrev_b32_e32 v33, 2, v33
	ds_bpermute_b32 v33, v33, v32
	s_add_i32 s12, s12, 0
	v_cmp_gt_u32_e32 vcc, 32, v154
	s_and_saveexec_b64 s[44:45], vcc
	s_cbranch_execz .LBB0_844
	s_waitcnt lgkmcnt(0)
	v_add_f32_e32 v32, v32, v33
	v_lshl_add_u32 v33, v153, 2, s12
	ds_write_b32 v33, v32 offset:34816
	s_branch .LBB0_844
